# v143 + attention suffix-product chain interleaved with exps/adds (dependency spacing)
# baseline (speedup 1.0000x reference)
; #define LAS __attribute__((address_space(3)))
; __device__ __forceinline__ void attn_unit(LAS unsigned char* lds, const bf16_t* Qm, const bf16_t* Km, const bf16_t* VT, const bf16_t* GBm, bf16_t* YB, int b, int hp, int qb) {
;     ...
;         if (k0 < qw + 15 && !__all(Rs == 0.f)) {
;             f32x4 s[4];
; #pragma unroll
;             for (int rb = 0; rb < 4; ++rb) {
;                 const int c = rb >> 1, e = rb & 1;
;                 const int kl = 32 * c + (fr >> 2) * 8 + e * 4 + (fr & 3);
;                 s[rb] = (f32x4){0.f, 0.f, 0.f, 0.f};
; #pragma unroll
;                 for (int ks = 0; ks < 4; ++ks) {
;                     const bf16x8 a = *(const LAS bf16x8*)(KL + kl * 272 + (ks * 32 + fq * 8) * 2);
;                     s[rb] = __builtin_amdgcn_mfma_f32_16x16x32_bf16(a, qf[ks], s[rb], 0, 0, 0);
;                 }
;             }
;             const int qi = qw + fr;
;             float be[2][8], om[2][8];
; #pragma unroll
;             for (int c = 0; c < 2; ++c)
; #pragma unroll
;                 for (int i = 0; i < 8; ++i) {
;                     const float z = s[2 * c + (i >> 2)][i & 3];
;                     const int key = k0 + 32 * c + 8 * fq + i;
;                     const float e = __builtin_amdgcn_exp2f(-fabsf(z));
;                     const float r = __builtin_amdgcn_rcpf(1.0f + e);
;                     const bool pos = z >= 0.f, valid = key < qi;
;                     be[c][i] = valid ? (pos ? r : e * r) : 0.f;
;                     om[c][i] = valid ? (pos ? e * r : r) : 1.f;
;                 }
;             float suf[2][8], Gs[2], Tt[2];
; #pragma unroll
;             for (int c = 0; c < 2; ++c) {
;                 float run = 1.f;
; #pragma unroll
;                 for (int i = 7; i >= 0; --i) { suf[c][i] = run; run *= om[c][i]; }
;                 const float t1 = __shfl(run, (lane + 16) & 63), t2 = __shfl(run, (lane + 32) & 63), t3 = __shfl(run, (lane + 48) & 63);
;                 Gs[c] = (fq < 3 ? t1 : 1.f) * (fq < 2 ? t2 : 1.f) * (fq < 1 ? t3 : 1.f);
;                 Tt[c] = (run * t1) * (t2 * t3);
;             }
.Lattn_nomask:
	ds_read_b128 v[120:123], v116
	ds_read_b128 v[124:127], v116 offset:64
	ds_read_b128 v[128:131], v116 offset:1088
	ds_read_b128 v[132:135], v116 offset:1152
	s_waitcnt lgkmcnt(3)
	v_mfma_f32_16x16x32_bf16 v[120:123], v[120:123], v[0:3], 0
	s_waitcnt lgkmcnt(2)
	v_mfma_f32_16x16x32_bf16 v[120:123], v[124:127], v[4:7], v[120:123]
	ds_read_b128 v[124:127], v116 offset:128
	ds_read_b128 v[136:139], v116 offset:192
	s_waitcnt lgkmcnt(3)
	v_mfma_f32_16x16x32_bf16 v[128:131], v[128:131], v[0:3], 0
	s_waitcnt lgkmcnt(1)
	v_mfma_f32_16x16x32_bf16 v[120:123], v[124:127], v[8:11], v[120:123]
	ds_read_b128 v[124:127], v116 offset:1216
	ds_read_b128 v[140:143], v116 offset:1280
	ds_read_b128 v[144:147], v116 offset:8704
	ds_read_b128 v[148:151], v116 offset:8768
	v_mfma_f32_16x16x32_bf16 v[128:131], v[132:135], v[4:7], v[128:131]
	ds_read_b128 v[132:135], v116 offset:8832
	ds_read_b128 v[152:155], v116 offset:8896
	ds_read_b128 v[156:159], v116 offset:9792
	ds_read_b128 v[160:163], v116 offset:9856
	s_waitcnt lgkmcnt(8)
	v_mfma_f32_16x16x32_bf16 v[120:123], v[136:139], v[12:15], v[120:123]
	ds_read_b128 v[136:139], v116 offset:9920
	ds_read_b128 v[164:167], v116 offset:9984
	s_waitcnt lgkmcnt(9)
	v_mfma_f32_16x16x32_bf16 v[124:127], v[124:127], v[8:11], v[128:131]
	s_nop 3
	v_exp_f32_e32 v97, v120
	s_nop 0
	v_add_f32_e32 v101, 1.0, v97
	s_waitcnt lgkmcnt(7)
	v_mfma_f32_16x16x32_bf16 v[128:131], v[144:147], v[0:3], 0
	v_rcp_f32_e32 v168, v101
	s_nop 0
	v_mul_f32_e32 v101, v97, v168
	s_waitcnt lgkmcnt(6)
	v_mfma_f32_16x16x32_bf16 v[128:131], v[148:151], v[4:7], v[128:131]
	v_mfma_f32_16x16x32_bf16 v[124:127], v[140:143], v[12:15], v[124:127]
	v_exp_f32_e32 v142, v121
	v_exp_f32_e32 v143, v122
	s_waitcnt lgkmcnt(5)
	v_mfma_f32_16x16x32_bf16 v[128:131], v[132:135], v[8:11], v[128:131]
	v_add_f32_e32 v103, 1.0, v142
	v_rcp_f32_e32 v103, v103
	s_waitcnt lgkmcnt(3)
	v_mfma_f32_16x16x32_bf16 v[132:135], v[156:159], v[0:3], 0
	v_add_f32_e32 v120, 1.0, v143
	v_rcp_f32_e32 v120, v120
	s_waitcnt lgkmcnt(2)
	v_mfma_f32_16x16x32_bf16 v[132:135], v[160:163], v[4:7], v[132:135]
	s_waitcnt lgkmcnt(1)
	v_mfma_f32_16x16x32_bf16 v[132:135], v[136:139], v[8:11], v[132:135]
	v_exp_f32_e32 v144, v123
	v_exp_f32_e32 v145, v124
	v_add_f32_e32 v121, 1.0, v144
	v_rcp_f32_e32 v121, v121
	v_add_f32_e32 v122, 1.0, v145
	v_rcp_f32_e32 v122, v122
	v_mfma_f32_16x16x32_bf16 v[128:131], v[152:155], v[12:15], v[128:131]
	s_nop 0
	s_nop 0
	v_exp_f32_e32 v146, v125
	s_nop 0
	v_add_f32_e32 v123, 1.0, v146
	v_rcp_f32_e32 v123, v123
	s_nop 0
	s_nop 0
	v_exp_f32_e32 v138, v128
	v_exp_f32_e32 v131, v131
	v_exp_f32_e32 v126, v126
	s_nop 0
	v_add_f32_e32 v124, 1.0, v126
	v_rcp_f32_e32 v124, v124
	s_waitcnt lgkmcnt(0)
	v_mfma_f32_16x16x32_bf16 v[132:135], v[164:167], v[12:15], v[132:135]
	v_exp_f32_e32 v127, v127
	s_nop 0
	v_add_f32_e32 v125, 1.0, v127
	v_rcp_f32_e32 v147, v125
	v_add_f32_e32 v136, 1.0, v138
	v_rcp_f32_e32 v140, v136
	v_exp_f32_e32 v129, v129
	v_exp_f32_e32 v130, v130
	v_mul_f32_e32 v128, v138, v140
	v_add_f32_e32 v125, 1.0, v129
	v_add_f32_e32 v136, 1.0, v130
	v_add_f32_e32 v137, 1.0, v131
	v_rcp_f32_e32 v125, v125
	v_rcp_f32_e32 v141, v136
	v_rcp_f32_e32 v148, v137
	v_mul_f32_e32 v153, v147, v124
	v_exp_f32_e32 v132, v132
	v_mul_f32_e32 v154, v123, v153
	v_exp_f32_e32 v133, v133
	v_mul_f32_e32 v155, v122, v154
	v_exp_f32_e32 v134, v134
	v_mul_f32_e32 v156, v121, v155
	v_exp_f32_e32 v99, v135
	v_add_f32_e32 v136, 1.0, v132
	v_mul_f32_e32 v157, v120, v156
	v_add_f32_e32 v137, 1.0, v133
	v_mul_f32_e32 v103, v103, v157
	v_add_f32_e32 v138, 1.0, v134
	v_or_b32_e32 v135, v105, v107
	v_add_f32_e32 v139, 1.0, v99
	v_rcp_f32_e32 v149, v136
	v_rcp_f32_e32 v150, v137
	v_rcp_f32_e32 v152, v138
	v_rcp_f32_e32 v151, v139
	v_mul_f32_e32 v136, v168, v103
	v_lshlrev_b32_e32 v135, 2, v135
	v_xor_b32_e32 v135, 0x80, v135
	v_mul_f32_e32 v152, v151, v152
	ds_bpermute_b32 v137, v135, v136
	ds_bpermute_b32 v138, v118, v136
	v_mul_f32_e32 v150, v150, v152
	v_mul_f32_e32 v149, v149, v150
	v_mul_f32_e32 v148, v148, v149
	v_mul_f32_e32 v158, v141, v148
	v_mul_f32_e32 v159, v125, v158
	ds_bpermute_b32 v139, v119, v136
	s_waitcnt lgkmcnt(2)
	v_cndmask_b32_e64 v97, 1.0, v137, s[10:11]
	s_waitcnt lgkmcnt(1)
; #define LAS __attribute__((address_space(3)))
; __device__ __forceinline__ unsigned cvt_pk_bf16(float lo, float hi) { unsigned r; asm volatile("v_cvt_pk_bf16_f32 %0, %1, %2" : "=v"(r) : "v"(lo), "v"(hi)); return r; }
; __device__ __forceinline__ void attn_unit(LAS unsigned char* lds, const bf16_t* Qm, const bf16_t* Km, const bf16_t* VT, const bf16_t* GBm, bf16_t* YB, int b, int hp, int qb) {
;     ...
;                 const float t1 = __shfl(run, (lane + 16) & 63), t2 = __shfl(run, (lane + 32) & 63), t3 = __shfl(run, (lane + 48) & 63);
;                 Gs[c] = (fq < 3 ? t1 : 1.f) * (fq < 2 ? t2 : 1.f) * (fq < 1 ? t3 : 1.f);
;                 Tt[c] = (run * t1) * (t2 * t3);
;             }
;             bf16x8 pf[2];
; #pragma unroll
;             for (int c = 0; c < 2; ++c) {
;                 const float basec = Rs * Gs[c] * (c == 0 ? Tt[1] : 1.f);
;                 float w[8];
; #pragma unroll
;                 for (int i = 0; i < 8; ++i) w[i] = be[c][i] * (suf[c][i] * basec);
;                 u32x4 pw; pw.x = cvt_pk_bf16(w[0], w[1]); pw.y = cvt_pk_bf16(w[2], w[3]); pw.z = cvt_pk_bf16(w[4], w[5]); pw.w = cvt_pk_bf16(w[6], w[7]);
;                 pf[c] = __builtin_bit_cast(bf16x8, pw);
;             }
;             Rs *= Tt[0] * Tt[1];
; #pragma unroll
;             for (int db = 0; db < 8; ++db)
; #pragma unroll
;                 for (int c = 0; c < 2; ++c) {
;                     const bf16x8 a = *(const LAS bf16x8*)(VL + (db * 16 + fr) * 144 + (32 * c + 8 * fq) * 2);
;                     o[db] = __builtin_amdgcn_mfma_f32_16x16x32_bf16(a, pf[c], o[db], 0, 0, 0);
;                 }
	v_cndmask_b32_e64 v120, v138, 1.0, s[0:1]
	v_mul_f32_e32 v121, v140, v159
	v_mul_f32_e32 v97, v120, v97
	ds_bpermute_b32 v120, v135, v121
	ds_bpermute_b32 v123, v118, v121
	ds_bpermute_b32 v122, v119, v121
	s_waitcnt lgkmcnt(3)
	v_cndmask_b32_e64 v124, 1.0, v139, s[4:5]
	v_mul_f32_e32 v124, v97, v124
	s_waitcnt lgkmcnt(2)
	v_cndmask_b32_e64 v97, 1.0, v120, s[10:11]
	s_waitcnt lgkmcnt(1)
	v_cndmask_b32_e64 v125, v123, 1.0, s[0:1]
	v_mul_f32_e32 v97, v125, v97
	s_waitcnt lgkmcnt(0)
	v_cndmask_b32_e64 v125, 1.0, v122, s[4:5]
	v_mul_f32_e32 v120, v120, v122
	v_mul_f32_e32 v121, v121, v123
	v_mul_f32_e32 v135, v97, v125
	v_mul_f32_e32 v140, v96, v124
	v_mul_f32_e32 v141, v120, v121
	v_mul_f32_e32 v97, v140, v141
	v_mul_f32_e32 v228, v103, v97
	v_mul_f32_e32 v229, v157, v97
	v_mul_f32_e32 v230, v156, v97
	v_mul_f32_e32 v231, v155, v97
	v_mul_f32_e32 v232, v154, v97
	v_mul_f32_e32 v233, v153, v97
	v_mul_f32_e32 v234, v147, v97
	v_mul_f32_e32 v101, v101, v228
	v_mul_f32_e32 v103, v142, v228
	v_mul_f32_e32 v121, v143, v229
	v_mul_f32_e32 v122, v144, v230
	v_mul_f32_e32 v123, v145, v231
	v_mul_f32_e32 v124, v146, v232
	v_mul_f32_e32 v125, v126, v233
	v_mul_f32_e32 v97, v127, v234
	v_cvt_pk_bf16_f32 v120, v101, v103
	v_cvt_pk_bf16_f32 v121, v121, v122
	v_cvt_pk_bf16_f32 v122, v123, v124
	v_cvt_pk_bf16_f32 v123, v125, v97
	v_mul_f32_e32 v97, v96, v135
	v_mul_f32_e32 v228, v97, v159
	v_mul_f32_e32 v229, v97, v158
	v_mul_f32_e32 v230, v97, v148
	v_mul_f32_e32 v231, v97, v149
	v_mul_f32_e32 v232, v97, v150
	v_mul_f32_e32 v233, v97, v152
	v_mul_f32_e32 v234, v151, v97
	v_mul_f32_e32 v101, v128, v228
	v_mul_f32_e32 v103, v129, v228
	v_mul_f32_e32 v125, v130, v229
	v_mul_f32_e32 v126, v131, v230
	v_mul_f32_e32 v127, v132, v231
	v_mul_f32_e32 v128, v133, v232
	v_mul_f32_e32 v129, v134, v233
	v_mul_f32_e32 v97, v99, v234
	v_cvt_pk_bf16_f32 v124, v101, v103
	v_cvt_pk_bf16_f32 v125, v125, v126
	v_cvt_pk_bf16_f32 v126, v127, v128
	v_cvt_pk_bf16_f32 v127, v129, v97
	ds_read_b128 v[128:131], v117 offset:17408
	ds_read_b128 v[132:135], v117 offset:17472
	s_waitcnt lgkmcnt(1)
	v_mfma_f32_16x16x32_bf16 v[60:63], v[128:131], v[120:123], v[60:63]
	ds_read_b128 v[128:131], v117 offset:19712
	s_waitcnt lgkmcnt(1)
	v_mfma_f32_16x16x32_bf16 v[60:63], v[132:135], v[124:127], v[60:63]
	ds_read_b128 v[132:135], v117 offset:19776
	s_waitcnt lgkmcnt(1)
	v_mfma_f32_16x16x32_bf16 v[72:75], v[128:131], v[120:123], v[72:75]
	ds_read_b128 v[128:131], v117 offset:22016
	s_waitcnt lgkmcnt(1)
	v_mfma_f32_16x16x32_bf16 v[72:75], v[132:135], v[124:127], v[72:75]
	ds_read_b128 v[132:135], v117 offset:22080
	s_waitcnt lgkmcnt(1)
	v_mfma_f32_16x16x32_bf16 v[56:59], v[128:131], v[120:123], v[56:59]
	ds_read_b128 v[128:131], v117 offset:24320
	s_waitcnt lgkmcnt(1)
	v_mfma_f32_16x16x32_bf16 v[56:59], v[132:135], v[124:127], v[56:59]
	ds_read_b128 v[132:135], v117 offset:24384
	s_waitcnt lgkmcnt(1)
	v_mfma_f32_16x16x32_bf16 v[44:47], v[128:131], v[120:123], v[44:47]
	ds_read_b128 v[128:131], v117 offset:26624
	s_waitcnt lgkmcnt(1)
	v_mfma_f32_16x16x32_bf16 v[44:47], v[132:135], v[124:127], v[44:47]
	ds_read_b128 v[132:135], v117 offset:26688
	s_waitcnt lgkmcnt(1)
	v_mfma_f32_16x16x32_bf16 v[32:35], v[128:131], v[120:123], v[32:35]
	ds_read_b128 v[128:131], v117 offset:28928
	s_waitcnt lgkmcnt(1)
	v_mfma_f32_16x16x32_bf16 v[32:35], v[132:135], v[124:127], v[32:35]
	ds_read_b128 v[132:135], v117 offset:28992
	s_waitcnt lgkmcnt(1)
	v_mfma_f32_16x16x32_bf16 v[24:27], v[128:131], v[120:123], v[24:27]
	ds_read_b128 v[128:131], v117 offset:31232
	s_waitcnt lgkmcnt(1)
	v_mfma_f32_16x16x32_bf16 v[24:27], v[132:135], v[124:127], v[24:27]
	ds_read_b128 v[132:135], v117 offset:31296
	s_waitcnt lgkmcnt(1)
	v_mfma_f32_16x16x32_bf16 v[20:23], v[128:131], v[120:123], v[20:23]
	ds_read_b128 v[128:131], v117 offset:33536
	s_waitcnt lgkmcnt(1)
	v_mfma_f32_16x16x32_bf16 v[20:23], v[132:135], v[124:127], v[20:23]
	ds_read_b128 v[132:135], v117 offset:33600
	s_waitcnt lgkmcnt(1)
	v_mfma_f32_16x16x32_bf16 v[16:19], v[128:131], v[120:123], v[16:19]
	v_mul_f32_e64 v120, v136, v138
	v_mul_f32_e64 v121, v137, v139
	v_mul_f32_e32 v97, v120, v121
	s_waitcnt lgkmcnt(0)
	v_mfma_f32_16x16x32_bf16 v[16:19], v[132:135], v[124:127], v[16:19]
	v_mul_f32_e32 v97, v97, v141
	v_mul_f32_e32 v96, v96, v97
